# v39 + nt hint on the out-proj epilogue's x (f32 residual) loads only
# speedup vs baseline: 1.0095x; 1.0095x over previous
;     __device__ __forceinline__ void operator()(Acc& acc, const Unit& u, int wr, int wc, int fr, int fq, PG8_LAS unsigned char*, const Pre&) const {
;     ...
;         for (int ai = 0; ai < 2; ++ai) {
;             f32x4 xv[4][2][2]; float sb[4], ss[4];
; #pragma unroll
;             for (int m = 0; m < 4; ++m) { const int row = u.pm * 256 + ai * 128 + wr * 64 + m * 16 + fr; sb[m] = ssq1[2 * (size_t)row + 1]; ss[m] = 0.f;
; #pragma unroll
;                 for (int bj = 0; bj < 2; ++bj)
; #pragma unroll
;                     for (int n = 0; n < 2; ++n) xv[m][bj][n] = *(const f32x4*)(x + (size_t)row * DM + col0 + bj * 128 + n * 16); }
; #pragma unroll
;             for (int m = 0; m < 4; ++m) sb[m] = rsqrtf(sb[m] * (1.0f / 512.0f) + EPS);
;             const int col_st = u.pn * 256 + wc * 32 + ((fq & 1) ? 16 + 4 * (fq - 1) : 4 * fq);
; #pragma unroll
;             for (int bj = 0; bj < 2; ++bj) {
;                 const f32x4 gv0 = *(const f32x4*)(g1p + bj * 128), gv1 = *(const f32x4*)(g1p + bj * 128 + 16);
;                 const f32x4 gm0 = *(const f32x4*)(n2g + col0 + bj * 128) * (*(const f32x4*)(g1p + 2 * DM + bj * 128) + 1.0f);
;                 const f32x4 gm1 = *(const f32x4*)(n2g + col0 + bj * 128 + 16) * (*(const f32x4*)(g1p + 2 * DM + bj * 128 + 16) + 1.0f);
.LBB0_835:
	s_lshl_b32 s6, s58, 8
	global_load_dword v1, v[132:133], off offset:4
	s_or_b32 s9, s6, s73
	v_add_u32_e32 v2, s9, v243
	v_ashrrev_i32_e32 v3, 31, v2
	v_lshlrev_b64 v[204:205], 2, v[2:3]
	v_lshl_add_u64 v[228:229], s[20:21], 0, v[204:205]
	v_lshlrev_b64 v[132:133], 12, v[222:223]
	v_or_b32_e32 v236, 16, v222
	v_lshl_add_u64 v[132:133], v[228:229], 0, v[132:133]
	v_ashrrev_i32_e32 v237, 31, v236
	global_load_dwordx4 v[200:203], v[132:133], off nt
	global_load_dwordx4 v[196:199], v[132:133], off offset:64 nt
	global_load_dwordx4 v[160:163], v[132:133], off offset:512 nt
	global_load_dwordx4 v[156:159], v[132:133], off offset:576 nt
	v_lshl_add_u64 v[132:133], v[236:237], 3, s[28:29]
	global_load_dword v180, v[132:133], off offset:4
	v_lshlrev_b64 v[132:133], 12, v[236:237]
	v_or_b32_e32 v234, 32, v222
	v_lshl_add_u64 v[132:133], v[228:229], 0, v[132:133]
	v_ashrrev_i32_e32 v235, 31, v234
	global_load_dwordx4 v[192:195], v[132:133], off nt
	global_load_dwordx4 v[184:187], v[132:133], off offset:64 nt
	global_load_dwordx4 v[152:155], v[132:133], off offset:512 nt
	global_load_dwordx4 v[148:151], v[132:133], off offset:576 nt
	v_lshl_add_u64 v[132:133], v[234:235], 3, s[28:29]
	global_load_dword v181, v[132:133], off offset:4
	v_lshlrev_b64 v[132:133], 12, v[234:235]
	v_or_b32_e32 v232, 48, v222
	v_lshl_add_u64 v[132:133], v[228:229], 0, v[132:133]
	v_ashrrev_i32_e32 v233, 31, v232
	global_load_dwordx4 v[176:179], v[132:133], off nt
	global_load_dwordx4 v[172:175], v[132:133], off offset:64 nt
	global_load_dwordx4 v[144:147], v[132:133], off offset:512 nt
	global_load_dwordx4 v[140:143], v[132:133], off offset:576 nt
	v_lshl_add_u64 v[132:133], v[232:233], 3, s[28:29]
	global_load_dword v182, v[132:133], off offset:4
	s_ashr_i32 s8, s56, 4
	s_mul_i32 s6, s8, 0x6000
	s_mul_hi_i32 s7, s8, 0x6000
	s_add_u32 s6, s18, s6
	s_addc_u32 s7, s19, s7
	v_lshl_add_u64 v[224:225], s[6:7], 0, v[204:205]
	v_lshlrev_b64 v[132:133], 12, v[232:233]
	v_lshl_add_u64 v[132:133], v[228:229], 0, v[132:133]
	v_lshl_add_u64 v[2:3], v[224:225], 0, s[38:39]
	global_load_dwordx4 v[168:171], v[132:133], off nt
	global_load_dwordx4 v[164:167], v[132:133], off offset:64 nt
	global_load_dwordx4 v[136:139], v[132:133], off offset:512 nt
	s_nop 0
	global_load_dwordx4 v[132:135], v[132:133], off offset:576 nt
	v_lshl_add_u64 v[230:231], s[22:23], 0, v[204:205]
	v_add_u32_e32 v226, s9, v245
	v_ashrrev_i32_e32 v227, 31, v226
	s_mul_i32 s7, s8, 0xa00000
	s_mul_hi_i32 s6, s8, 0xa00000
	s_add_u32 s12, s76, s7
	s_addc_u32 s13, s77, s6
	s_waitcnt vmcnt(0)
	v_fmamk_f32 v1, v1, 0x3b000000, v252
	v_cmp_gt_f32_e32 vcc, s80, v1
	v_mul_f32_e32 v183, 0x4b800000, v1
	s_nop 0
	v_cndmask_b32_e32 v1, v1, v183, vcc
	v_rsq_f32_e32 v1, v1
	s_nop 0
	v_mul_f32_e32 v183, 0x45800000, v1
	v_cndmask_b32_e32 v244, v1, v183, vcc
	v_pk_mul_f32 v[128:129], v[128:129], v[244:245] op_sel_hi:[1,0]
	v_fmamk_f32 v1, v180, 0x3b000000, v252
	v_cmp_gt_f32_e32 vcc, s80, v1
	v_mul_f32_e32 v180, 0x4b800000, v1
	v_pk_mul_f32 v[130:131], v[130:131], v[244:245] op_sel_hi:[1,0]
	v_cndmask_b32_e32 v1, v1, v180, vcc
	v_rsq_f32_e32 v1, v1
	v_pk_mul_f32 v[124:125], v[124:125], v[244:245] op_sel_hi:[1,0]
	v_pk_mul_f32 v[126:127], v[126:127], v[244:245] op_sel_hi:[1,0]
	v_pk_mul_f32 v[96:97], v[96:97], v[244:245] op_sel_hi:[1,0]
	v_mul_f32_e32 v180, 0x45800000, v1
	v_cndmask_b32_e32 v242, v1, v180, vcc
	v_fmamk_f32 v1, v181, 0x3b000000, v252
	v_cmp_gt_f32_e32 vcc, s80, v1
	v_mul_f32_e32 v180, 0x4b800000, v1
	v_pk_mul_f32 v[98:99], v[98:99], v[244:245] op_sel_hi:[1,0]
	v_cndmask_b32_e32 v1, v1, v180, vcc
	v_rsq_f32_e32 v1, v1
	v_pk_mul_f32 v[92:93], v[92:93], v[244:245] op_sel_hi:[1,0]
	v_pk_mul_f32 v[94:95], v[94:95], v[244:245] op_sel_hi:[1,0]
	v_pk_mul_f32 v[90:91], v[90:91], v[242:243] op_sel_hi:[1,0]
	v_mul_f32_e32 v180, 0x45800000, v1
	v_cndmask_b32_e32 v240, v1, v180, vcc
	v_fmamk_f32 v1, v182, 0x3b000000, v252
	v_cmp_gt_f32_e32 vcc, s80, v1
	v_mul_f32_e32 v180, 0x4b800000, v1
	v_pk_mul_f32 v[110:111], v[110:111], v[240:241] op_sel_hi:[1,0]
	v_cndmask_b32_e32 v1, v1, v180, vcc
	v_rsq_f32_e32 v1, v1
	v_pk_mul_f32 v[108:109], v[108:109], v[240:241] op_sel_hi:[1,0]
	v_pk_mul_f32 v[88:89], v[88:89], v[242:243] op_sel_hi:[1,0]
	v_pk_mul_f32 v[86:87], v[86:87], v[242:243] op_sel_hi:[1,0]
	v_mul_f32_e32 v180, 0x45800000, v1
	v_cndmask_b32_e32 v238, v1, v180, vcc
	v_add_co_u32_e32 v180, vcc, s71, v224
	v_pk_mul_f32 v[104:105], v[104:105], v[238:239] op_sel_hi:[1,0]
	s_nop 0
	v_addc_co_u32_e32 v181, vcc, 0, v225, vcc
	v_add_co_u32_e32 v246, vcc, s72, v224
	global_load_dwordx4 v[188:191], v[180:181], off
	s_nop 0
	global_load_dwordx4 v[180:183], v[2:3], off offset:64
	v_addc_co_u32_e32 v247, vcc, 0, v225, vcc
	global_load_dwordx4 v[208:211], v[246:247], off
	global_load_dwordx4 v[204:207], v[230:231], off
	v_pk_mul_f32 v[106:107], v[106:107], v[238:239] op_sel_hi:[1,0]
	v_pk_mul_f32 v[100:101], v[100:101], v[238:239] op_sel_hi:[1,0]
	v_pk_mul_f32 v[102:103], v[102:103], v[238:239] op_sel_hi:[1,0]
	v_pk_mul_f32 v[84:85], v[84:85], v[242:243] op_sel_hi:[1,0]
	v_pk_mul_f32 v[82:83], v[82:83], v[240:241] op_sel_hi:[1,0]
	v_pk_mul_f32 v[80:81], v[80:81], v[240:241] op_sel_hi:[1,0]
	v_pk_mul_f32 v[78:79], v[78:79], v[240:241] op_sel_hi:[1,0]
	v_pk_mul_f32 v[76:77], v[76:77], v[240:241] op_sel_hi:[1,0]
	v_pk_mul_f32 v[74:75], v[74:75], v[238:239] op_sel_hi:[1,0]
	v_pk_mul_f32 v[72:73], v[72:73], v[238:239] op_sel_hi:[1,0]
	v_pk_mul_f32 v[70:71], v[70:71], v[238:239] op_sel_hi:[1,0]
	v_pk_mul_f32 v[68:69], v[68:69], v[238:239] op_sel_hi:[1,0]
	s_waitcnt vmcnt(3)
; __device__ __forceinline__ unsigned cvtpk(float lo, float hi) { f32x2 v = {lo, hi}; bf16x2_t b = __builtin_convertvector(v, bf16x2_t); return __builtin_bit_cast(unsigned, b); }
;     __device__ __forceinline__ void operator()(Acc& acc, const Unit& u, int wr, int wc, int fr, int fq, PG8_LAS unsigned char*, const Pre&) const {
;     ...
;             const int col_st = u.pn * 256 + wc * 32 + ((fq & 1) ? 16 + 4 * (fq - 1) : 4 * fq);
; #pragma unroll
;             for (int bj = 0; bj < 2; ++bj) {
;                 const f32x4 gv0 = *(const f32x4*)(g1p + bj * 128), gv1 = *(const f32x4*)(g1p + bj * 128 + 16);
;                 const f32x4 gm0 = *(const f32x4*)(n2g + col0 + bj * 128) * (*(const f32x4*)(g1p + 2 * DM + bj * 128) + 1.0f);
;                 const f32x4 gm1 = *(const f32x4*)(n2g + col0 + bj * 128 + 16) * (*(const f32x4*)(g1p + 2 * DM + bj * 128 + 16) + 1.0f);
; #pragma unroll
;                 for (int m = 0; m < 4; ++m) {
;                     const int row = u.pm * 256 + ai * 128 + wr * 64 + m * 16 + fr;
;                     const f32x4 o0 = xv[m][bj][0] + gv0 * (acc[ai][bj][m][0] * sb[m]), o1 = xv[m][bj][1] + gv1 * (acc[ai][bj][m][1] * sb[m]);
;                     ss[m] += ((o0[0] * o0[0] + o0[1] * o0[1]) + (o0[2] * o0[2] + o0[3] * o0[3])) + ((o1[0] * o1[0] + o1[1] * o1[1]) + (o1[2] * o1[2] + o1[3] * o1[3]));
;                     const f32x4 a0 = o0 * gm0, a1 = o1 * gm1;
;                     u32x2 x0, x1, y0, y1;
;                     x0.x = cvtpk(o0[0], o0[1]); x0.y = cvtpk(o0[2], o0[3]); x1.x = cvtpk(o1[0], o1[1]); x1.y = cvtpk(o1[2], o1[3]);
;                     y0.x = cvtpk(a0[0], a0[1]); y0.y = cvtpk(a0[2], a0[3]); y1.x = cvtpk(a1[0], a1[1]); y1.y = cvtpk(a1[2], a1[3]);
;                     const size_t off = (size_t)row * DM + col_st + bj * 128;
;                     *(u32x4*)(XN + (size_t)b * (SEQ * (INC - DM)) + off) = pair16(x0, x1);
;                     *(u32x4*)(A2 + off) = pair16(y0, y1);
;                 }
	v_pk_fma_f32 v[130:131], v[130:131], v[190:191], v[202:203]
	v_pk_fma_f32 v[128:129], v[128:129], v[188:189], v[200:201]
	s_waitcnt vmcnt(2)
	v_pk_fma_f32 v[198:199], v[126:127], v[182:183], v[198:199]
	v_pk_fma_f32 v[126:127], v[124:125], v[180:181], v[196:197]
	s_waitcnt vmcnt(1)
	v_pk_add_f32 v[210:211], v[210:211], 1.0 op_sel_hi:[1,0]
	v_pk_add_f32 v[208:209], v[208:209], 1.0 op_sel_hi:[1,0]
	s_waitcnt vmcnt(0)
	v_pk_mul_f32 v[248:249], v[206:207], v[210:211]
	v_pk_mul_f32 v[250:251], v[204:205], v[208:209]
	global_load_dwordx4 v[204:207], v[230:231], off offset:64
	global_load_dwordx4 v[208:211], v[246:247], off offset:64
	v_mul_f32_e32 v1, v129, v129
	v_mul_f32_e32 v124, v131, v131
	v_fmac_f32_e32 v1, v128, v128
	v_fmac_f32_e32 v124, v130, v130
	v_add_f32_e32 v1, v1, v124
	v_mul_f32_e32 v124, v127, v127
	v_mul_f32_e32 v125, v199, v199
	v_fmac_f32_e32 v124, v126, v126
	v_fmac_f32_e32 v125, v198, v198
	v_add_f32_e32 v124, v124, v125
	v_pk_mul_f32 v[196:197], v[130:131], v[248:249]
	v_add_f32_e32 v1, v1, v124
	v_pk_mul_f32 v[200:201], v[128:129], v[250:251]
	v_cvt_pk_bf16_f32 v124, v128, v129
	v_cvt_pk_bf16_f32 v129, v196, v197
	v_lshlrev_b64 v[196:197], 10, v[222:223]
	v_cvt_pk_bf16_f32 v125, v130, v131
	v_cvt_pk_bf16_f32 v128, v200, v201
	v_pk_fma_f32 v[110:111], v[110:111], v[182:183], v[174:175]
	v_pk_fma_f32 v[164:165], v[180:181], v[100:101], v[164:165]
	s_waitcnt vmcnt(0)
	v_pk_add_f32 v[210:211], v[210:211], 1.0 op_sel_hi:[1,0]
	v_pk_add_f32 v[208:209], v[208:209], 1.0 op_sel_hi:[1,0]
	v_pk_mul_f32 v[206:207], v[206:207], v[210:211]
	v_pk_mul_f32 v[204:205], v[204:205], v[208:209]
	v_pk_mul_f32 v[202:203], v[198:199], v[206:207]
	v_pk_mul_f32 v[208:209], v[126:127], v[204:205]
	v_cvt_pk_bf16_f32 v126, v126, v127
	v_cvt_pk_bf16_f32 v127, v198, v199
	v_lshl_add_u64 v[198:199], v[196:197], 0, v[226:227]
	v_lshlrev_b64 v[200:201], 1, v[198:199]
	v_cvt_pk_bf16_f32 v130, v208, v209
	v_cvt_pk_bf16_f32 v131, v202, v203
	v_permlane16_swap_b32_e32 v124, v126
	v_permlane16_swap_b32_e32 v125, v127
	v_lshl_add_u64 v[198:199], s[12:13], 0, v[200:201]
	global_store_dwordx4 v[198:199], v[124:127], off
	v_permlane16_swap_b32_e32 v128, v130
	v_permlane16_swap_b32_e32 v129, v131
	v_lshl_add_u64 v[124:125], s[34:35], 0, v[200:201]
	global_store_dwordx4 v[124:125], v[128:131], off
	v_pk_mul_f32 v[124:125], v[120:121], v[242:243] op_sel_hi:[1,0]
	v_pk_mul_f32 v[120:121], v[122:123], v[242:243] op_sel_hi:[1,0]
	v_pk_fma_f32 v[122:123], v[124:125], v[188:189], v[192:193]
	v_pk_mul_f32 v[124:125], v[116:117], v[242:243] op_sel_hi:[1,0]
	v_pk_mul_f32 v[116:117], v[118:119], v[242:243] op_sel_hi:[1,0]
	v_pk_fma_f32 v[120:121], v[120:121], v[190:191], v[194:195]
	v_pk_fma_f32 v[116:117], v[116:117], v[182:183], v[186:187]
	v_pk_fma_f32 v[118:119], v[124:125], v[180:181], v[184:185]
	v_pk_mul_f32 v[130:131], v[120:121], v[248:249]
	v_pk_mul_f32 v[128:129], v[122:123], v[250:251]
	v_pk_mul_f32 v[184:185], v[116:117], v[206:207]
	v_pk_mul_f32 v[186:187], v[118:119], v[204:205]
	v_cvt_pk_bf16_f32 v128, v128, v129
	v_cvt_pk_bf16_f32 v129, v130, v131
	v_cvt_pk_bf16_f32 v131, v184, v185
	v_lshlrev_b64 v[184:185], 10, v[236:237]
	v_cvt_pk_bf16_f32 v130, v186, v187
	v_lshl_add_u64 v[186:187], v[184:185], 0, v[226:227]
	v_cvt_pk_bf16_f32 v124, v122, v123
	v_cvt_pk_bf16_f32 v125, v120, v121
	v_cvt_pk_bf16_f32 v126, v118, v119
	v_cvt_pk_bf16_f32 v127, v116, v117
	v_lshlrev_b64 v[192:193], 1, v[186:187]
	v_permlane16_swap_b32_e32 v124, v126
	v_permlane16_swap_b32_e32 v125, v127
	v_lshl_add_u64 v[186:187], s[12:13], 0, v[192:193]
	global_store_dwordx4 v[186:187], v[124:127], off
	v_permlane16_swap_b32_e32 v128, v130
	v_permlane16_swap_b32_e32 v129, v131
	v_lshl_add_u64 v[124:125], s[34:35], 0, v[192:193]
	global_store_dwordx4 v[124:125], v[128:131], off
	v_pk_mul_f32 v[124:125], v[112:113], v[240:241] op_sel_hi:[1,0]
	v_pk_mul_f32 v[112:113], v[114:115], v[240:241] op_sel_hi:[1,0]
	v_pk_fma_f32 v[114:115], v[188:189], v[124:125], v[176:177]
	v_pk_fma_f32 v[112:113], v[190:191], v[112:113], v[178:179]
	v_pk_fma_f32 v[124:125], v[108:109], v[180:181], v[172:173]
	v_pk_mul_f32 v[172:173], v[110:111], v[206:207]
	v_pk_mul_f32 v[108:109], v[112:113], v[248:249]
	v_cvt_pk_bf16_f32 v179, v172, v173
	v_lshlrev_b64 v[172:173], 10, v[234:235]
	v_cvt_pk_bf16_f32 v177, v108, v109
	v_lshl_add_u64 v[108:109], v[172:173], 0, v[226:227]
	v_pk_mul_f32 v[174:175], v[124:125], v[204:205]
	v_cvt_pk_bf16_f32 v126, v114, v115
	v_cvt_pk_bf16_f32 v127, v112, v113
	v_cvt_pk_bf16_f32 v128, v124, v125
	v_cvt_pk_bf16_f32 v129, v110, v111
	v_lshlrev_b64 v[108:109], 1, v[108:109]
	v_pk_mul_f32 v[130:131], v[114:115], v[250:251]
	v_cvt_pk_bf16_f32 v178, v174, v175
	v_permlane16_swap_b32_e32 v126, v128
	v_permlane16_swap_b32_e32 v127, v129
	v_lshl_add_u64 v[174:175], s[12:13], 0, v[108:109]
	v_cvt_pk_bf16_f32 v176, v130, v131
	global_store_dwordx4 v[174:175], v[126:129], off
	v_pk_fma_f32 v[130:131], v[188:189], v[104:105], v[168:169]
	v_permlane16_swap_b32_e32 v176, v178
	v_pk_fma_f32 v[126:127], v[190:191], v[106:107], v[170:171]
	v_permlane16_swap_b32_e32 v177, v179
	v_lshl_add_u64 v[108:109], s[34:35], 0, v[108:109]
	v_pk_fma_f32 v[128:129], v[182:183], v[102:103], v[166:167]
	v_pk_mul_f32 v[106:107], v[248:249], v[126:127]
	v_pk_mul_f32 v[104:105], v[250:251], v[130:131]
	v_pk_mul_f32 v[166:167], v[204:205], v[164:165]
	global_store_dwordx4 v[108:109], v[176:179], off
	v_pk_mul_f32 v[108:109], v[206:207], v[128:129]
	v_cvt_pk_bf16_f32 v104, v104, v105
	v_cvt_pk_bf16_f32 v105, v106, v107
	v_cvt_pk_bf16_f32 v106, v166, v167
	v_lshlrev_b64 v[166:167], 10, v[232:233]
	v_cvt_pk_bf16_f32 v107, v108, v109
	v_lshl_add_u64 v[108:109], v[166:167], 0, v[226:227]
	v_cvt_pk_bf16_f32 v100, v130, v131
	v_cvt_pk_bf16_f32 v101, v126, v127
	v_cvt_pk_bf16_f32 v102, v164, v165
	v_cvt_pk_bf16_f32 v103, v128, v129
	v_lshlrev_b64 v[108:109], 1, v[108:109]
	v_permlane16_swap_b32_e32 v100, v102
	v_permlane16_swap_b32_e32 v101, v103
	v_lshl_add_u64 v[168:169], s[12:13], 0, v[108:109]
	global_store_dwordx4 v[168:169], v[100:103], off
	v_permlane16_swap_b32_e32 v104, v106
	v_permlane16_swap_b32_e32 v105, v107
	v_lshl_add_u64 v[100:101], s[34:35], 0, v[108:109]
	global_store_dwordx4 v[100:101], v[104:107], off
	global_load_dwordx4 v[104:107], v[2:3], off offset:512
	s_nop 0
	global_load_dwordx4 v[100:103], v[2:3], off offset:576
	global_load_dwordx4 v[176:179], v[230:231], off offset:512
	global_load_dwordx4 v[180:183], v[246:247], off offset:512
	s_waitcnt vmcnt(3)
; __device__ __forceinline__ unsigned cvtpk(float lo, float hi) { f32x2 v = {lo, hi}; bf16x2_t b = __builtin_convertvector(v, bf16x2_t); return __builtin_bit_cast(unsigned, b); }
;     __device__ __forceinline__ void operator()(Acc& acc, const Unit& u, int wr, int wc, int fr, int fq, PG8_LAS unsigned char*, const Pre&) const {
;     ...
;             for (int bj = 0; bj < 2; ++bj) {
;                 const f32x4 gv0 = *(const f32x4*)(g1p + bj * 128), gv1 = *(const f32x4*)(g1p + bj * 128 + 16);
;                 const f32x4 gm0 = *(const f32x4*)(n2g + col0 + bj * 128) * (*(const f32x4*)(g1p + 2 * DM + bj * 128) + 1.0f);
;                 const f32x4 gm1 = *(const f32x4*)(n2g + col0 + bj * 128 + 16) * (*(const f32x4*)(g1p + 2 * DM + bj * 128 + 16) + 1.0f);
; #pragma unroll
;                 for (int m = 0; m < 4; ++m) {
;                     const int row = u.pm * 256 + ai * 128 + wr * 64 + m * 16 + fr;
;                     const f32x4 o0 = xv[m][bj][0] + gv0 * (acc[ai][bj][m][0] * sb[m]), o1 = xv[m][bj][1] + gv1 * (acc[ai][bj][m][1] * sb[m]);
;                     ss[m] += ((o0[0] * o0[0] + o0[1] * o0[1]) + (o0[2] * o0[2] + o0[3] * o0[3])) + ((o1[0] * o1[0] + o1[1] * o1[1]) + (o1[2] * o1[2] + o1[3] * o1[3]));
;                     const f32x4 a0 = o0 * gm0, a1 = o1 * gm1;
;                     u32x2 x0, x1, y0, y1;
;                     x0.x = cvtpk(o0[0], o0[1]); x0.y = cvtpk(o0[2], o0[3]); x1.x = cvtpk(o1[0], o1[1]); x1.y = cvtpk(o1[2], o1[3]);
;                     y0.x = cvtpk(a0[0], a0[1]); y0.y = cvtpk(a0[2], a0[3]); y1.x = cvtpk(a1[0], a1[1]); y1.y = cvtpk(a1[2], a1[3]);
;                     const size_t off = (size_t)row * DM + col_st + bj * 128;
;                     *(u32x4*)(XN + (size_t)b * (SEQ * (INC - DM)) + off) = pair16(x0, x1);
;                     *(u32x4*)(A2 + off) = pair16(y0, y1);
;                 }
;             }
; #pragma unroll
;             for (int m = 0; m < 4; ++m) { const int row = u.pm * 256 + ai * 128 + wr * 64 + m * 16 + fr; float t = fq_sum(ss[m]); if (fq == 0) atomicAdd(ssq2 + row, t); }
	v_pk_fma_f32 v[98:99], v[98:99], v[106:107], v[162:163]
	v_pk_fma_f32 v[96:97], v[96:97], v[104:105], v[160:161]
	s_waitcnt vmcnt(2)
	v_pk_fma_f32 v[158:159], v[94:95], v[102:103], v[158:159]
	s_waitcnt vmcnt(0)
	v_pk_add_f32 v[108:109], v[182:183], 1.0 op_sel_hi:[1,0]
	v_pk_add_f32 v[180:181], v[180:181], 1.0 op_sel_hi:[1,0]
	v_pk_mul_f32 v[170:171], v[178:179], v[108:109]
	v_pk_mul_f32 v[176:177], v[176:177], v[180:181]
	global_load_dwordx4 v[178:181], v[230:231], off offset:576
	global_load_dwordx4 v[188:191], v[246:247], off offset:576
	v_pk_fma_f32 v[94:95], v[92:93], v[100:101], v[156:157]
	v_mul_f32_e32 v92, v97, v97
	v_mul_f32_e32 v93, v99, v99
	v_fmac_f32_e32 v92, v96, v96
	v_fmac_f32_e32 v93, v98, v98
	v_add_f32_e32 v92, v92, v93
	v_mul_f32_e32 v93, v95, v95
	v_mul_f32_e32 v156, v159, v159
	v_fmac_f32_e32 v93, v94, v94
	v_fmac_f32_e32 v156, v158, v158
	v_add_f32_e32 v93, v93, v156
	v_add_f32_e32 v92, v92, v93
	v_add_f32_e32 v1, v1, v92
	v_pk_mul_f32 v[156:157], v[98:99], v[170:171]
	v_pk_mul_f32 v[160:161], v[96:97], v[176:177]
	v_cvt_pk_bf16_f32 v92, v96, v97
	v_cvt_pk_bf16_f32 v93, v98, v99
	v_cvt_pk_bf16_f32 v96, v160, v161
	v_cvt_pk_bf16_f32 v97, v156, v157
	v_pk_fma_f32 v[88:89], v[88:89], v[104:105], v[152:153]
	v_pk_fma_f32 v[90:91], v[90:91], v[106:107], v[154:155]
	v_pk_fma_f32 v[84:85], v[84:85], v[100:101], v[148:149]
	v_pk_fma_f32 v[86:87], v[86:87], v[102:103], v[150:151]
	v_pk_fma_f32 v[80:81], v[80:81], v[104:105], v[144:145]
	v_pk_fma_f32 v[82:83], v[82:83], v[106:107], v[146:147]
	v_pk_fma_f32 v[76:77], v[76:77], v[100:101], v[140:141]
	v_pk_fma_f32 v[78:79], v[78:79], v[102:103], v[142:143]
	v_pk_fma_f32 v[72:73], v[72:73], v[104:105], v[136:137]
	v_pk_fma_f32 v[74:75], v[74:75], v[106:107], v[138:139]
	v_pk_fma_f32 v[68:69], v[68:69], v[100:101], v[132:133]
	v_pk_fma_f32 v[70:71], v[70:71], v[102:103], v[134:135]
	s_waitcnt vmcnt(0)
	v_pk_add_f32 v[108:109], v[190:191], 1.0 op_sel_hi:[1,0]
	v_pk_add_f32 v[182:183], v[188:189], 1.0 op_sel_hi:[1,0]
	v_pk_mul_f32 v[180:181], v[180:181], v[108:109]
	v_pk_mul_f32 v[178:179], v[178:179], v[182:183]
	v_lshl_add_u64 v[108:109], v[226:227], 0, s[36:37]
	v_pk_mul_f32 v[162:163], v[158:159], v[180:181]
	v_pk_mul_f32 v[182:183], v[94:95], v[178:179]
	v_cvt_pk_bf16_f32 v94, v94, v95
	v_cvt_pk_bf16_f32 v95, v158, v159
	v_cvt_pk_bf16_f32 v98, v182, v183
	v_cvt_pk_bf16_f32 v99, v162, v163
	v_lshl_add_u64 v[156:157], v[108:109], 0, v[196:197]
	v_permlane16_swap_b32_e32 v92, v94
	v_permlane16_swap_b32_e32 v93, v95
	global_store_dwordx4 v[198:199], v[92:95], off offset:256
	v_permlane16_swap_b32_e32 v96, v98
	v_permlane16_swap_b32_e32 v97, v99
	v_lshl_add_u64 v[92:93], v[156:157], 1, s[34:35]
	global_store_dwordx4 v[92:93], v[96:99], off
	v_pk_mul_f32 v[148:149], v[86:87], v[180:181]
	v_pk_mul_f32 v[150:151], v[84:85], v[178:179]
	v_pk_mul_f32 v[98:99], v[90:91], v[170:171]
	v_pk_mul_f32 v[96:97], v[88:89], v[176:177]
	v_cvt_pk_bf16_f32 v92, v88, v89
	v_cvt_pk_bf16_f32 v93, v90, v91
	v_cvt_pk_bf16_f32 v94, v84, v85
	v_cvt_pk_bf16_f32 v95, v86, v87
	v_cvt_pk_bf16_f32 v96, v96, v97
	v_cvt_pk_bf16_f32 v97, v98, v99
	v_cvt_pk_bf16_f32 v98, v150, v151
	v_cvt_pk_bf16_f32 v99, v148, v149
	v_lshl_add_u64 v[148:149], v[108:109], 0, v[184:185]
	v_permlane16_swap_b32_e32 v92, v94
	v_permlane16_swap_b32_e32 v93, v95
	global_store_dwordx4 v[186:187], v[92:95], off offset:256
	v_permlane16_swap_b32_e32 v96, v98
	v_permlane16_swap_b32_e32 v97, v99
	v_lshl_add_u64 v[92:93], v[148:149], 1, s[34:35]
	global_store_dwordx4 v[92:93], v[96:99], off
	v_pk_mul_f32 v[140:141], v[78:79], v[180:181]
	v_pk_mul_f32 v[142:143], v[76:77], v[178:179]
	v_pk_mul_f32 v[98:99], v[82:83], v[170:171]
	v_pk_mul_f32 v[96:97], v[80:81], v[176:177]
	v_cvt_pk_bf16_f32 v92, v80, v81
	v_cvt_pk_bf16_f32 v93, v82, v83
	v_cvt_pk_bf16_f32 v94, v76, v77
	v_cvt_pk_bf16_f32 v95, v78, v79
	v_cvt_pk_bf16_f32 v96, v96, v97
	v_cvt_pk_bf16_f32 v97, v98, v99
	v_cvt_pk_bf16_f32 v98, v142, v143
	v_cvt_pk_bf16_f32 v99, v140, v141
	v_lshl_add_u64 v[140:141], v[108:109], 0, v[172:173]
	v_permlane16_swap_b32_e32 v92, v94
	v_permlane16_swap_b32_e32 v93, v95
	global_store_dwordx4 v[174:175], v[92:95], off offset:256
	v_permlane16_swap_b32_e32 v96, v98
	v_permlane16_swap_b32_e32 v97, v99
	v_lshl_add_u64 v[92:93], v[140:141], 1, s[34:35]
	global_store_dwordx4 v[92:93], v[96:99], off
	v_pk_mul_f32 v[100:101], v[70:71], v[180:181]
	v_pk_mul_f32 v[102:103], v[68:69], v[178:179]
	v_pk_mul_f32 v[98:99], v[74:75], v[170:171]
	v_pk_mul_f32 v[96:97], v[72:73], v[176:177]
	v_cvt_pk_bf16_f32 v92, v72, v73
	v_cvt_pk_bf16_f32 v93, v74, v75
	v_cvt_pk_bf16_f32 v94, v68, v69
	v_cvt_pk_bf16_f32 v95, v70, v71
	v_cvt_pk_bf16_f32 v96, v96, v97
	v_cvt_pk_bf16_f32 v97, v98, v99
	v_cvt_pk_bf16_f32 v98, v102, v103
	v_cvt_pk_bf16_f32 v99, v100, v101
	v_lshl_add_u64 v[100:101], v[108:109], 0, v[166:167]
	v_permlane16_swap_b32_e32 v92, v94
	v_permlane16_swap_b32_e32 v93, v95
	global_store_dwordx4 v[168:169], v[92:95], off offset:256
	v_permlane16_swap_b32_e32 v96, v98
	v_permlane16_swap_b32_e32 v97, v99
	v_lshl_add_u64 v[92:93], v[100:101], 1, s[34:35]
	global_store_dwordx4 v[92:93], v[96:99], off
	v_mov_b32_e32 v92, v1
	s_nop 1
	v_permlane16_swap_b32_e32 v1, v92
	v_add_f32_e32 v1, v1, v92
	v_mov_b32_e32 v92, v1
	s_nop 1
	v_permlane32_swap_b32_e32 v1, v92
	s_and_saveexec_b64 s[6:7], s[2:3]
	s_cbranch_execz .LBB0_837
	v_lshl_add_u64 v[94:95], v[222:223], 2, s[30:31]
	v_add_f32_e32 v1, v1, v92
	global_atomic_add_f32 v[94:95], v1, off

;     __device__ __forceinline__ void operator()(Acc& acc, const Unit& u, int wr, int wc, int fr, int fq, PG8_LAS unsigned char*, const Pre&) const {
;     ...
;         for (int ai = 0; ai < 2; ++ai) {
;             f32x4 xv[4][2][2]; float sb[4], ss[4];
; #pragma unroll
;             for (int m = 0; m < 4; ++m) { const int row = u.pm * 256 + ai * 128 + wr * 64 + m * 16 + fr; sb[m] = ssq1[2 * (size_t)row + 1]; ss[m] = 0.f;
; #pragma unroll
;                 for (int bj = 0; bj < 2; ++bj)
; #pragma unroll
;                     for (int n = 0; n < 2; ++n) xv[m][bj][n] = *(const f32x4*)(x + (size_t)row * DM + col0 + bj * 128 + n * 16); }
; #pragma unroll
;             for (int m = 0; m < 4; ++m) sb[m] = rsqrtf(sb[m] * (1.0f / 512.0f) + EPS);
;             const int col_st = u.pn * 256 + wc * 32 + ((fq & 1) ? 16 + 4 * (fq - 1) : 4 * fq);
; #pragma unroll
;             for (int bj = 0; bj < 2; ++bj) {
;                 const f32x4 gv0 = *(const f32x4*)(g1p + bj * 128), gv1 = *(const f32x4*)(g1p + bj * 128 + 16);
;                 const f32x4 gm0 = *(const f32x4*)(n2g + col0 + bj * 128) * (*(const f32x4*)(g1p + 2 * DM + bj * 128) + 1.0f);
;                 const f32x4 gm1 = *(const f32x4*)(n2g + col0 + bj * 128 + 16) * (*(const f32x4*)(g1p + 2 * DM + bj * 128 + 16) + 1.0f);
; #pragma unroll
;                 for (int m = 0; m < 4; ++m) {
;                     const int row = u.pm * 256 + ai * 128 + wr * 64 + m * 16 + fr;
;                     const f32x4 o0 = xv[m][bj][0] + gv0 * (acc[ai][bj][m][0] * sb[m]), o1 = xv[m][bj][1] + gv1 * (acc[ai][bj][m][1] * sb[m]);
;                     ss[m] += ((o0[0] * o0[0] + o0[1] * o0[1]) + (o0[2] * o0[2] + o0[3] * o0[3])) + ((o1[0] * o1[0] + o1[1] * o1[1]) + (o1[2] * o1[2] + o1[3] * o1[3]));
;                     const f32x4 a0 = o0 * gm0, a1 = o1 * gm1;
;                     u32x2 x0, x1, y0, y1;
;                     x0.x = cvtpk(o0[0], o0[1]); x0.y = cvtpk(o0[2], o0[3]); x1.x = cvtpk(o1[0], o1[1]); x1.y = cvtpk(o1[2], o1[3]);
;                     y0.x = cvtpk(a0[0], a0[1]); y0.y = cvtpk(a0[2], a0[3]); y1.x = cvtpk(a1[0], a1[1]); y1.y = cvtpk(a1[2], a1[3]);
;                     const size_t off = (size_t)row * DM + col_st + bj * 128;
;                     *(u32x4*)(XN + (size_t)b * (SEQ * (INC - DM)) + off) = pair16(x0, x1);
;                     *(u32x4*)(A2 + off) = pair16(y0, y1);
.LBB0_843:
	s_or_b64 exec, exec, s[6:7]
	v_add_u32_e32 v116, 0x80, v222
	v_ashrrev_i32_e32 v117, 31, v116
	v_add_u32_e32 v112, 0x90, v222
	v_lshl_add_u64 v[72:73], v[116:117], 3, s[28:29]
	v_ashrrev_i32_e32 v113, 31, v112
	v_add_u32_e32 v114, 0xa0, v222
	v_lshl_add_u64 v[68:69], v[224:225], 0, s[40:41]
	global_load_dword v1, v[72:73], off offset:4
	v_lshl_add_u64 v[72:73], v[112:113], 3, s[28:29]
	v_ashrrev_i32_e32 v115, 31, v114
	v_add_u32_e32 v110, 0xb0, v222
	v_lshl_add_u64 v[70:71], v[224:225], 0, s[42:43]
	global_load_dword v178, v[72:73], off offset:4
	global_load_dwordx4 v[118:121], v[68:69], off nt
	v_lshl_add_u64 v[68:69], v[114:115], 3, s[28:29]
	v_ashrrev_i32_e32 v111, 31, v110
	global_load_dwordx4 v[126:129], v[70:71], off nt
	global_load_dwordx4 v[130:133], v[230:231], off
	global_load_dwordx4 v[134:137], v[230:231], off offset:64
	global_load_dword v179, v[68:69], off offset:4
	v_lshl_add_u64 v[68:69], v[110:111], 3, s[28:29]
	global_load_dword v180, v[68:69], off offset:4
	v_lshlrev_b64 v[68:69], 12, v[116:117]
	v_lshl_add_u64 v[68:69], v[228:229], 0, v[68:69]
	global_load_dwordx4 v[138:141], v[68:69], off nt
	global_load_dwordx4 v[104:107], v[2:3], off
	global_load_dwordx4 v[100:103], v[2:3], off offset:64
	global_load_dwordx4 v[142:145], v[68:69], off offset:64 nt
	v_lshlrev_b64 v[70:71], 12, v[112:113]
	v_lshlrev_b64 v[72:73], 12, v[114:115]
	v_lshlrev_b64 v[74:75], 12, v[110:111]
	v_lshl_add_u64 v[70:71], v[228:229], 0, v[70:71]
	v_lshl_add_u64 v[72:73], v[228:229], 0, v[72:73]
	v_lshl_add_u64 v[122:123], v[228:229], 0, v[74:75]
	global_load_dwordx4 v[96:99], v[68:69], off offset:512 nt
	global_load_dwordx4 v[92:95], v[68:69], off offset:576 nt
	global_load_dwordx4 v[146:149], v[70:71], off nt
	global_load_dwordx4 v[150:153], v[70:71], off offset:64 nt
	global_load_dwordx4 v[88:91], v[70:71], off offset:512 nt
	global_load_dwordx4 v[84:87], v[70:71], off offset:576 nt
	global_load_dwordx4 v[154:157], v[72:73], off nt
	global_load_dwordx4 v[158:161], v[72:73], off offset:64 nt
	global_load_dwordx4 v[80:83], v[72:73], off offset:512 nt
	global_load_dwordx4 v[76:79], v[72:73], off offset:576 nt
	global_load_dwordx4 v[162:165], v[122:123], off nt
	global_load_dwordx4 v[166:169], v[122:123], off offset:64 nt
	s_nop 0
	global_load_dwordx4 v[72:75], v[122:123], off offset:512 nt
	global_load_dwordx4 v[68:71], v[122:123], off offset:576 nt
	v_lshl_add_u64 v[124:125], v[224:225], 0, s[44:45]
	s_waitcnt vmcnt(25)
	v_fmamk_f32 v1, v1, 0x3b000000, v252
	v_cmp_gt_f32_e32 vcc, s80, v1
	s_waitcnt vmcnt(23)
	v_pk_add_f32 v[120:121], v[120:121], 1.0 op_sel_hi:[1,0]
	v_pk_add_f32 v[118:119], v[118:119], 1.0 op_sel_hi:[1,0]
	s_waitcnt vmcnt(22)
	v_pk_add_f32 v[126:127], v[126:127], 1.0 op_sel_hi:[1,0]
	s_waitcnt vmcnt(21)
	v_pk_mul_f32 v[170:171], v[132:133], v[120:121]
	v_mul_f32_e32 v121, 0x4b800000, v1
	s_waitcnt vmcnt(20)
	v_pk_mul_f32 v[176:177], v[134:135], v[126:127]
	s_waitcnt vmcnt(18)
	v_fmamk_f32 v120, v180, 0x3b000000, v252
	v_mul_f32_e32 v126, 0x4b800000, v120
	v_cndmask_b32_e32 v1, v1, v121, vcc
	v_cmp_gt_f32_e64 s[10:11], s80, v120
	v_rsq_f32_e32 v1, v1
	v_pk_add_f32 v[122:123], v[128:129], 1.0 op_sel_hi:[1,0]
	v_cndmask_b32_e64 v120, v120, v126, s[10:11]
	v_rsq_f32_e32 v121, v120
	v_mul_f32_e32 v120, 0x45800000, v1
	v_pk_mul_f32 v[172:173], v[130:131], v[118:119]
	v_fmamk_f32 v118, v178, 0x3b000000, v252
	v_mul_f32_e32 v127, 0x45800000, v121
	v_cndmask_b32_e32 v126, v1, v120, vcc
	v_pk_mul_f32 v[174:175], v[136:137], v[122:123]
	v_fmamk_f32 v119, v179, 0x3b000000, v252
	v_mul_f32_e32 v122, 0x4b800000, v118
	v_cmp_gt_f32_e64 s[6:7], s80, v118
	v_pk_mul_f32 v[66:67], v[66:67], v[126:127] op_sel_hi:[1,0]
	v_mul_f32_e32 v123, 0x4b800000, v119
	v_cndmask_b32_e64 v118, v118, v122, s[6:7]
	v_cmp_gt_f32_e64 s[8:9], s80, v119
	v_pk_mul_f32 v[64:65], v[64:65], v[126:127] op_sel_hi:[1,0]
	v_pk_mul_f32 v[60:61], v[60:61], v[126:127] op_sel_hi:[1,0]
	s_waitcnt vmcnt(16)
	v_pk_fma_f32 v[178:179], v[66:67], v[106:107], v[140:141]
	v_cndmask_b32_e64 v119, v119, v123, s[8:9]
	v_rsq_f32_e32 v118, v118
	v_pk_mul_f32 v[62:63], v[62:63], v[126:127] op_sel_hi:[1,0]
	v_pk_fma_f32 v[180:181], v[64:65], v[104:105], v[138:139]
	s_waitcnt vmcnt(14)
	v_pk_fma_f32 v[184:185], v[60:61], v[100:101], v[142:143]
	v_pk_mul_f32 v[60:61], v[178:179], v[170:171]
	v_rsq_f32_e32 v119, v119
	v_pk_fma_f32 v[182:183], v[62:63], v[102:103], v[144:145]
	v_pk_mul_f32 v[62:63], v[180:181], v[172:173]
	v_cvt_pk_bf16_f32 v129, v60, v61
	v_lshlrev_b64 v[60:61], 10, v[116:117]
	v_pk_mul_f32 v[132:133], v[182:183], v[174:175]
	v_pk_mul_f32 v[130:131], v[184:185], v[176:177]
	v_cvt_pk_bf16_f32 v128, v62, v63
	v_lshl_add_u64 v[62:63], v[60:61], 0, v[226:227]
	v_cvt_pk_bf16_f32 v64, v180, v181
	v_cvt_pk_bf16_f32 v65, v178, v179
	v_cvt_pk_bf16_f32 v66, v184, v185
	v_cvt_pk_bf16_f32 v67, v182, v183
	v_cvt_pk_bf16_f32 v130, v130, v131
	v_cvt_pk_bf16_f32 v131, v132, v133
	v_lshlrev_b64 v[132:133], 1, v[62:63]
	v_mul_f32_e32 v122, 0x45800000, v118
	v_permlane16_swap_b32_e32 v64, v66
	v_permlane16_swap_b32_e32 v65, v67
	v_lshl_add_u64 v[62:63], s[12:13], 0, v[132:133]
	v_mul_f32_e32 v123, 0x45800000, v119
	v_cndmask_b32_e64 v122, v118, v122, s[6:7]
	global_store_dwordx4 v[62:63], v[64:67], off
	v_permlane16_swap_b32_e32 v128, v130
	v_permlane16_swap_b32_e32 v129, v131
	v_lshl_add_u64 v[64:65], s[34:35], 0, v[132:133]
	global_store_dwordx4 v[64:65], v[128:131], off
	v_pk_mul_f32 v[64:65], v[56:57], v[122:123] op_sel_hi:[1,0]
	v_pk_mul_f32 v[56:57], v[58:59], v[122:123] op_sel_hi:[1,0]
	s_waitcnt vmcnt(13)
; __device__ __forceinline__ unsigned cvtpk(float lo, float hi) { f32x2 v = {lo, hi}; bf16x2_t b = __builtin_convertvector(v, bf16x2_t); return __builtin_bit_cast(unsigned, b); }
;     __device__ __forceinline__ void operator()(Acc& acc, const Unit& u, int wr, int wc, int fr, int fq, PG8_LAS unsigned char*, const Pre&) const {
;     ...
;             for (int bj = 0; bj < 2; ++bj) {
;                 const f32x4 gv0 = *(const f32x4*)(g1p + bj * 128), gv1 = *(const f32x4*)(g1p + bj * 128 + 16);
;                 const f32x4 gm0 = *(const f32x4*)(n2g + col0 + bj * 128) * (*(const f32x4*)(g1p + 2 * DM + bj * 128) + 1.0f);
;                 const f32x4 gm1 = *(const f32x4*)(n2g + col0 + bj * 128 + 16) * (*(const f32x4*)(g1p + 2 * DM + bj * 128 + 16) + 1.0f);
; #pragma unroll
;                 for (int m = 0; m < 4; ++m) {
;                     const int row = u.pm * 256 + ai * 128 + wr * 64 + m * 16 + fr;
;                     const f32x4 o0 = xv[m][bj][0] + gv0 * (acc[ai][bj][m][0] * sb[m]), o1 = xv[m][bj][1] + gv1 * (acc[ai][bj][m][1] * sb[m]);
;                     ss[m] += ((o0[0] * o0[0] + o0[1] * o0[1]) + (o0[2] * o0[2] + o0[3] * o0[3])) + ((o1[0] * o1[0] + o1[1] * o1[1]) + (o1[2] * o1[2] + o1[3] * o1[3]));
;                     const f32x4 a0 = o0 * gm0, a1 = o1 * gm1;
;                     u32x2 x0, x1, y0, y1;
;                     x0.x = cvtpk(o0[0], o0[1]); x0.y = cvtpk(o0[2], o0[3]); x1.x = cvtpk(o1[0], o1[1]); x1.y = cvtpk(o1[2], o1[3]);
;                     y0.x = cvtpk(a0[0], a0[1]); y0.y = cvtpk(a0[2], a0[3]); y1.x = cvtpk(a1[0], a1[1]); y1.y = cvtpk(a1[2], a1[3]);
;                     const size_t off = (size_t)row * DM + col_st + bj * 128;
;                     *(u32x4*)(XN + (size_t)b * (SEQ * (INC - DM)) + off) = pair16(x0, x1);
;                     *(u32x4*)(A2 + off) = pair16(y0, y1);
	v_pk_fma_f32 v[58:59], v[64:65], v[104:105], v[146:147]
	v_pk_fma_f32 v[56:57], v[56:57], v[106:107], v[148:149]
	v_pk_mul_f32 v[64:65], v[52:53], v[122:123] op_sel_hi:[1,0]
	v_pk_mul_f32 v[52:53], v[54:55], v[122:123] op_sel_hi:[1,0]
	s_waitcnt vmcnt(12)
	v_pk_fma_f32 v[54:55], v[64:65], v[100:101], v[150:151]
	v_pk_mul_f32 v[64:65], v[56:57], v[170:171]
	v_pk_fma_f32 v[52:53], v[52:53], v[102:103], v[152:153]
	v_pk_mul_f32 v[66:67], v[58:59], v[172:173]
	v_cvt_pk_bf16_f32 v133, v64, v65
	v_lshlrev_b64 v[64:65], 10, v[112:113]
	v_pk_mul_f32 v[136:137], v[52:53], v[174:175]
	v_pk_mul_f32 v[134:135], v[54:55], v[176:177]
	v_cvt_pk_bf16_f32 v132, v66, v67
	v_lshl_add_u64 v[66:67], v[64:65], 0, v[226:227]
	v_cvt_pk_bf16_f32 v128, v58, v59
	v_cvt_pk_bf16_f32 v129, v56, v57
	v_cvt_pk_bf16_f32 v130, v54, v55
	v_cvt_pk_bf16_f32 v131, v52, v53
	v_cvt_pk_bf16_f32 v134, v134, v135
	v_cvt_pk_bf16_f32 v135, v136, v137
	v_lshlrev_b64 v[136:137], 1, v[66:67]
	v_permlane16_swap_b32_e32 v128, v130
	v_permlane16_swap_b32_e32 v129, v131
	v_lshl_add_u64 v[66:67], s[12:13], 0, v[136:137]
	v_cndmask_b32_e64 v120, v119, v123, s[8:9]
	global_store_dwordx4 v[66:67], v[128:131], off
	v_permlane16_swap_b32_e32 v132, v134
	v_permlane16_swap_b32_e32 v133, v135
	v_lshl_add_u64 v[128:129], s[34:35], 0, v[136:137]
	global_store_dwordx4 v[128:129], v[132:135], off
	v_pk_mul_f32 v[128:129], v[48:49], v[120:121] op_sel_hi:[1,0]
	v_pk_mul_f32 v[48:49], v[50:51], v[120:121] op_sel_hi:[1,0]
	s_waitcnt vmcnt(11)
	v_pk_fma_f32 v[50:51], v[104:105], v[128:129], v[154:155]
	v_pk_fma_f32 v[48:49], v[106:107], v[48:49], v[156:157]
	v_pk_mul_f32 v[128:129], v[44:45], v[120:121] op_sel_hi:[1,0]
	v_pk_mul_f32 v[44:45], v[46:47], v[120:121] op_sel_hi:[1,0]
	s_waitcnt vmcnt(10)
	v_pk_fma_f32 v[46:47], v[128:129], v[100:101], v[158:159]
	v_pk_mul_f32 v[128:129], v[48:49], v[170:171]
	v_pk_fma_f32 v[44:45], v[44:45], v[102:103], v[160:161]
	v_pk_mul_f32 v[130:131], v[50:51], v[172:173]
	v_cvt_pk_bf16_f32 v137, v128, v129
	v_lshlrev_b64 v[128:129], 10, v[114:115]
	v_pk_mul_f32 v[140:141], v[44:45], v[174:175]
	v_pk_mul_f32 v[138:139], v[46:47], v[176:177]
	v_cvt_pk_bf16_f32 v136, v130, v131
	v_lshl_add_u64 v[130:131], v[128:129], 0, v[226:227]
	v_cvt_pk_bf16_f32 v132, v50, v51
	v_cvt_pk_bf16_f32 v133, v48, v49
	v_cvt_pk_bf16_f32 v134, v46, v47
	v_cvt_pk_bf16_f32 v135, v44, v45
	v_cvt_pk_bf16_f32 v138, v138, v139
	v_cvt_pk_bf16_f32 v139, v140, v141
	v_lshlrev_b64 v[140:141], 1, v[130:131]
	v_permlane16_swap_b32_e32 v132, v134
	v_permlane16_swap_b32_e32 v133, v135
	v_lshl_add_u64 v[130:131], s[12:13], 0, v[140:141]
	v_cndmask_b32_e64 v118, v121, v127, s[10:11]
	global_store_dwordx4 v[130:131], v[132:135], off
	v_permlane16_swap_b32_e32 v136, v138
	v_permlane16_swap_b32_e32 v137, v139
	v_lshl_add_u64 v[132:133], s[34:35], 0, v[140:141]
	global_store_dwordx4 v[132:133], v[136:139], off
	v_pk_mul_f32 v[132:133], v[40:41], v[118:119] op_sel_hi:[1,0]
	v_pk_mul_f32 v[40:41], v[42:43], v[118:119] op_sel_hi:[1,0]
	s_waitcnt vmcnt(9)
	v_pk_fma_f32 v[42:43], v[104:105], v[132:133], v[162:163]
	v_pk_fma_f32 v[40:41], v[106:107], v[40:41], v[164:165]
	v_pk_mul_f32 v[104:105], v[36:37], v[118:119] op_sel_hi:[1,0]
	v_pk_mul_f32 v[36:37], v[38:39], v[118:119] op_sel_hi:[1,0]
	s_waitcnt vmcnt(8)
	v_pk_fma_f32 v[38:39], v[100:101], v[104:105], v[166:167]
	v_pk_mul_f32 v[100:101], v[170:171], v[40:41]
	v_pk_fma_f32 v[36:37], v[102:103], v[36:37], v[168:169]
	v_pk_mul_f32 v[102:103], v[172:173], v[42:43]
	v_cvt_pk_bf16_f32 v133, v100, v101
	v_lshlrev_b64 v[100:101], 10, v[110:111]
	v_pk_mul_f32 v[136:137], v[174:175], v[36:37]
	v_pk_mul_f32 v[134:135], v[176:177], v[38:39]
	v_cvt_pk_bf16_f32 v132, v102, v103
	v_lshl_add_u64 v[102:103], v[100:101], 0, v[226:227]
	v_cvt_pk_bf16_f32 v104, v42, v43
	v_cvt_pk_bf16_f32 v105, v40, v41
	v_cvt_pk_bf16_f32 v106, v38, v39
	v_cvt_pk_bf16_f32 v107, v36, v37
	v_cvt_pk_bf16_f32 v134, v134, v135
	v_cvt_pk_bf16_f32 v135, v136, v137
	v_lshlrev_b64 v[136:137], 1, v[102:103]
	v_permlane16_swap_b32_e32 v104, v106
	v_permlane16_swap_b32_e32 v105, v107
	v_lshl_add_u64 v[102:103], s[12:13], 0, v[136:137]
	global_store_dwordx4 v[102:103], v[104:107], off
	v_permlane16_swap_b32_e32 v132, v134
	v_permlane16_swap_b32_e32 v133, v135
	v_lshl_add_u64 v[104:105], s[34:35], 0, v[136:137]
	global_store_dwordx4 v[104:105], v[132:135], off
	global_load_dwordx4 v[104:107], v[124:125], off nt
	s_nop 0
	global_load_dwordx4 v[132:135], v[230:231], off offset:512
	v_lshl_add_u64 v[124:125], v[224:225], 0, s[46:47]
	global_load_dwordx4 v[136:139], v[124:125], off nt
	global_load_dwordx4 v[140:143], v[230:231], off offset:576
	global_load_dwordx4 v[144:147], v[2:3], off offset:512
	global_load_dwordx4 v[148:151], v[2:3], off offset:576
	v_mul_f32_e32 v1, v181, v181
	v_mul_f32_e32 v2, v179, v179
	v_fmac_f32_e32 v1, v180, v180
	v_fmac_f32_e32 v2, v178, v178
	v_add_f32_e32 v1, v1, v2
	v_mul_f32_e32 v2, v185, v185
	v_mul_f32_e32 v3, v183, v183
	v_fmac_f32_e32 v2, v184, v184
	v_fmac_f32_e32 v3, v182, v182
	v_add_f32_e32 v2, v2, v3
	v_add_f32_e32 v1, v1, v2
	v_pk_mul_f32 v[28:29], v[28:29], v[126:127] op_sel_hi:[1,0]
	v_pk_mul_f32 v[30:31], v[30:31], v[126:127] op_sel_hi:[1,0]
	v_pk_mul_f32 v[26:27], v[26:27], v[122:123] op_sel_hi:[1,0]
	v_pk_mul_f32 v[22:23], v[22:23], v[122:123] op_sel_hi:[1,0]
	v_pk_mul_f32 v[20:21], v[20:21], v[122:123] op_sel_hi:[1,0]
	v_pk_mul_f32 v[18:19], v[18:19], v[120:121] op_sel_hi:[1,0]
	v_pk_mul_f32 v[16:17], v[16:17], v[120:121] op_sel_hi:[1,0]
	v_pk_mul_f32 v[14:15], v[14:15], v[120:121] op_sel_hi:[1,0]
	v_pk_mul_f32 v[12:13], v[12:13], v[120:121] op_sel_hi:[1,0]
	v_pk_mul_f32 v[10:11], v[10:11], v[118:119] op_sel_hi:[1,0]
	v_pk_mul_f32 v[8:9], v[8:9], v[118:119] op_sel_hi:[1,0]
	v_pk_mul_f32 v[6:7], v[6:7], v[118:119] op_sel_hi:[1,0]
	v_pk_mul_f32 v[4:5], v[4:5], v[118:119] op_sel_hi:[1,0]
	s_waitcnt vmcnt(5)
; __device__ __forceinline__ unsigned cvtpk(float lo, float hi) { f32x2 v = {lo, hi}; bf16x2_t b = __builtin_convertvector(v, bf16x2_t); return __builtin_bit_cast(unsigned, b); }
;     __device__ __forceinline__ void operator()(Acc& acc, const Unit& u, int wr, int wc, int fr, int fq, PG8_LAS unsigned char*, const Pre&) const {
;     ...
;             for (int bj = 0; bj < 2; ++bj) {
;                 const f32x4 gv0 = *(const f32x4*)(g1p + bj * 128), gv1 = *(const f32x4*)(g1p + bj * 128 + 16);
;                 const f32x4 gm0 = *(const f32x4*)(n2g + col0 + bj * 128) * (*(const f32x4*)(g1p + 2 * DM + bj * 128) + 1.0f);
;                 const f32x4 gm1 = *(const f32x4*)(n2g + col0 + bj * 128 + 16) * (*(const f32x4*)(g1p + 2 * DM + bj * 128 + 16) + 1.0f);
; #pragma unroll
;                 for (int m = 0; m < 4; ++m) {
;                     const int row = u.pm * 256 + ai * 128 + wr * 64 + m * 16 + fr;
;                     const f32x4 o0 = xv[m][bj][0] + gv0 * (acc[ai][bj][m][0] * sb[m]), o1 = xv[m][bj][1] + gv1 * (acc[ai][bj][m][1] * sb[m]);
;                     ss[m] += ((o0[0] * o0[0] + o0[1] * o0[1]) + (o0[2] * o0[2] + o0[3] * o0[3])) + ((o1[0] * o1[0] + o1[1] * o1[1]) + (o1[2] * o1[2] + o1[3] * o1[3]));
;                     const f32x4 a0 = o0 * gm0, a1 = o1 * gm1;
;                     u32x2 x0, x1, y0, y1;
;                     x0.x = cvtpk(o0[0], o0[1]); x0.y = cvtpk(o0[2], o0[3]); x1.x = cvtpk(o1[0], o1[1]); x1.y = cvtpk(o1[2], o1[3]);
;                     y0.x = cvtpk(a0[0], a0[1]); y0.y = cvtpk(a0[2], a0[3]); y1.x = cvtpk(a1[0], a1[1]); y1.y = cvtpk(a1[2], a1[3]);
;                     const size_t off = (size_t)row * DM + col_st + bj * 128;
;                     *(u32x4*)(XN + (size_t)b * (SEQ * (INC - DM)) + off) = pair16(x0, x1);
;                     *(u32x4*)(A2 + off) = pair16(y0, y1);
;                 }
;             }
; #pragma unroll
;             for (int m = 0; m < 4; ++m) { const int row = u.pm * 256 + ai * 128 + wr * 64 + m * 16 + fr; float t = fq_sum(ss[m]); if (fq == 0) atomicAdd(ssq2 + row, t); }
	v_pk_add_f32 v[2:3], v[106:107], 1.0 op_sel_hi:[1,0]
	v_pk_add_f32 v[104:105], v[104:105], 1.0 op_sel_hi:[1,0]
	s_waitcnt vmcnt(4)
	v_pk_mul_f32 v[106:107], v[134:135], v[2:3]
	s_waitcnt vmcnt(3)
	v_pk_add_f32 v[2:3], v[138:139], 1.0 op_sel_hi:[1,0]
	v_pk_mul_f32 v[104:105], v[132:133], v[104:105]
	s_waitcnt vmcnt(2)
	v_pk_mul_f32 v[132:133], v[142:143], v[2:3]
	v_pk_mul_f32 v[2:3], v[32:33], v[126:127] op_sel_hi:[1,0]
	v_pk_mul_f32 v[32:33], v[34:35], v[126:127] op_sel_hi:[1,0]
	s_waitcnt vmcnt(1)
	v_pk_fma_f32 v[2:3], v[2:3], v[144:145], v[96:97]
	v_pk_fma_f32 v[32:33], v[32:33], v[146:147], v[98:99]
	s_waitcnt vmcnt(0)
	v_pk_fma_f32 v[34:35], v[30:31], v[150:151], v[94:95]
	v_pk_fma_f32 v[30:31], v[28:29], v[148:149], v[92:93]
	v_mul_f32_e32 v28, v3, v3
	v_mul_f32_e32 v29, v33, v33
	v_fmac_f32_e32 v28, v2, v2
	v_fmac_f32_e32 v29, v32, v32
	v_add_f32_e32 v28, v28, v29
	v_mul_f32_e32 v29, v31, v31
	v_mul_f32_e32 v92, v35, v35
	v_pk_add_f32 v[124:125], v[136:137], 1.0 op_sel_hi:[1,0]
	v_fmac_f32_e32 v29, v30, v30
	v_fmac_f32_e32 v92, v34, v34
	v_pk_mul_f32 v[124:125], v[140:141], v[124:125]
	v_add_f32_e32 v29, v29, v92
	v_add_f32_e32 v28, v28, v29
	v_pk_mul_f32 v[92:93], v[32:33], v[106:107]
	v_pk_mul_f32 v[94:95], v[2:3], v[104:105]
	v_pk_mul_f32 v[96:97], v[34:35], v[132:133]
	v_pk_mul_f32 v[98:99], v[30:31], v[124:125]
	v_add_f32_e32 v1, v1, v28
	v_cvt_pk_bf16_f32 v28, v2, v3
	v_cvt_pk_bf16_f32 v29, v32, v33
	v_cvt_pk_bf16_f32 v30, v30, v31
	v_cvt_pk_bf16_f32 v31, v34, v35
	v_cvt_pk_bf16_f32 v32, v94, v95
	v_cvt_pk_bf16_f32 v33, v92, v93
	v_cvt_pk_bf16_f32 v34, v98, v99
	v_cvt_pk_bf16_f32 v35, v96, v97
	v_lshl_add_u64 v[2:3], v[108:109], 0, v[60:61]
	v_permlane16_swap_b32_e32 v28, v30
	v_permlane16_swap_b32_e32 v29, v31
	v_permlane16_swap_b32_e32 v32, v34
	v_permlane16_swap_b32_e32 v33, v35
	v_lshl_add_u64 v[2:3], v[2:3], 1, s[34:35]
	global_store_dwordx4 v[62:63], v[28:31], off offset:256
	global_store_dwordx4 v[2:3], v[32:35], off
	v_pk_mul_f32 v[2:3], v[24:25], v[122:123] op_sel_hi:[1,0]
	v_pk_fma_f32 v[24:25], v[26:27], v[146:147], v[90:91]
	v_pk_fma_f32 v[2:3], v[2:3], v[144:145], v[88:89]
	v_pk_fma_f32 v[20:21], v[20:21], v[148:149], v[84:85]
	v_pk_fma_f32 v[22:23], v[22:23], v[150:151], v[86:87]
	v_pk_mul_f32 v[32:33], v[24:25], v[106:107]
	v_pk_mul_f32 v[30:31], v[2:3], v[104:105]
	v_pk_mul_f32 v[34:35], v[22:23], v[132:133]
	v_pk_mul_f32 v[60:61], v[20:21], v[124:125]
	v_cvt_pk_bf16_f32 v26, v2, v3
	v_cvt_pk_bf16_f32 v27, v24, v25
	v_cvt_pk_bf16_f32 v28, v20, v21
	v_cvt_pk_bf16_f32 v29, v22, v23
	v_cvt_pk_bf16_f32 v30, v30, v31
	v_cvt_pk_bf16_f32 v31, v32, v33
	v_cvt_pk_bf16_f32 v32, v60, v61
	v_cvt_pk_bf16_f32 v33, v34, v35
	v_lshl_add_u64 v[34:35], v[108:109], 0, v[64:65]
	v_permlane16_swap_b32_e32 v26, v28
	v_permlane16_swap_b32_e32 v27, v29
	global_store_dwordx4 v[66:67], v[26:29], off offset:256
	v_permlane16_swap_b32_e32 v30, v32
	v_permlane16_swap_b32_e32 v31, v33
	v_lshl_add_u64 v[26:27], v[34:35], 1, s[34:35]
	v_pk_fma_f32 v[16:17], v[16:17], v[144:145], v[80:81]
	v_pk_fma_f32 v[18:19], v[18:19], v[146:147], v[82:83]
	v_pk_fma_f32 v[12:13], v[12:13], v[148:149], v[76:77]
	v_pk_fma_f32 v[14:15], v[14:15], v[150:151], v[78:79]
	global_store_dwordx4 v[26:27], v[30:33], off
	v_pk_mul_f32 v[34:35], v[14:15], v[132:133]
	v_pk_mul_f32 v[60:61], v[12:13], v[124:125]
	v_pk_mul_f32 v[32:33], v[18:19], v[106:107]
	v_pk_mul_f32 v[30:31], v[16:17], v[104:105]
	v_cvt_pk_bf16_f32 v26, v16, v17
	v_cvt_pk_bf16_f32 v27, v18, v19
	v_cvt_pk_bf16_f32 v28, v12, v13
	v_cvt_pk_bf16_f32 v29, v14, v15
	v_cvt_pk_bf16_f32 v30, v30, v31
	v_cvt_pk_bf16_f32 v31, v32, v33
	v_cvt_pk_bf16_f32 v32, v60, v61
	v_cvt_pk_bf16_f32 v33, v34, v35
	v_lshl_add_u64 v[34:35], v[108:109], 0, v[128:129]
	v_permlane16_swap_b32_e32 v26, v28
	v_permlane16_swap_b32_e32 v27, v29
	global_store_dwordx4 v[130:131], v[26:29], off offset:256
	v_permlane16_swap_b32_e32 v30, v32
	v_permlane16_swap_b32_e32 v31, v33
	v_lshl_add_u64 v[26:27], v[34:35], 1, s[34:35]
	v_pk_fma_f32 v[8:9], v[8:9], v[144:145], v[72:73]
	v_pk_fma_f32 v[10:11], v[10:11], v[146:147], v[74:75]
	v_pk_fma_f32 v[4:5], v[4:5], v[148:149], v[68:69]
	v_pk_fma_f32 v[6:7], v[6:7], v[150:151], v[70:71]
	global_store_dwordx4 v[26:27], v[30:33], off
	v_pk_mul_f32 v[34:35], v[6:7], v[132:133]
	v_pk_mul_f32 v[60:61], v[4:5], v[124:125]
	v_pk_mul_f32 v[32:33], v[10:11], v[106:107]
	v_pk_mul_f32 v[30:31], v[8:9], v[104:105]
	v_cvt_pk_bf16_f32 v26, v8, v9
	v_cvt_pk_bf16_f32 v27, v10, v11
	v_cvt_pk_bf16_f32 v28, v4, v5
	v_cvt_pk_bf16_f32 v29, v6, v7
	v_cvt_pk_bf16_f32 v30, v30, v31
	v_cvt_pk_bf16_f32 v31, v32, v33
	v_cvt_pk_bf16_f32 v32, v60, v61
	v_cvt_pk_bf16_f32 v33, v34, v35
	v_lshl_add_u64 v[34:35], v[108:109], 0, v[100:101]
	v_permlane16_swap_b32_e32 v26, v28
	v_permlane16_swap_b32_e32 v27, v29
	global_store_dwordx4 v[102:103], v[26:29], off offset:256
	v_permlane16_swap_b32_e32 v30, v32
	v_permlane16_swap_b32_e32 v31, v33
	v_lshl_add_u64 v[26:27], v[34:35], 1, s[34:35]
	global_store_dwordx4 v[26:27], v[30:33], off
	v_mov_b32_e32 v26, v1
	s_nop 1
	v_permlane16_swap_b32_e32 v1, v26
	v_add_f32_e32 v1, v1, v26
	v_mov_b32_e32 v26, v1
	s_nop 1
	v_permlane32_swap_b32_e32 v1, v26
	s_and_saveexec_b64 s[6:7], s[2:3]
	s_cbranch_execz .LBB0_845
	v_lshl_add_u64 v[28:29], v[116:117], 2, s[30:31]
	v_add_f32_e32 v1, v1, v26
	global_atomic_add_f32 v[28:29], v1, off
